# FoX waves 4-7 delayed 256 cycles per tile (stagger); redundant cooperative-groups sync skipped
# speedup vs baseline: 1.0025x; 1.0014x over previous
; __device__ __forceinline__ void attn_phase(lptr L, const Params& P, int layer) {
;     ...
;     __syncthreads();
; #pragma unroll 1
;     for (int p = blk; p < 512; p += G) {
; #pragma unroll 1
;         for (int j = 0; j < 2; ++j) {
;     ...
;             continue;
;     ...
;             const int bh = p >> 3, s = p & 7; fox_unit(L, P, bh >> 3, bh & 7, j ? 15 - s : s);
.LBB0_150:
	s_or_b64 exec, exec, s[0:1]
	v_readfirstlane_b32 s99, v193
	s_nop 3
	s_lshr_b32 s99, s99, 8
	v_writelane_b32 v255, s75, 57
	v_writelane_b32 v255, s78, 58
	v_readlane_b32 s56, v252, 5
	v_readlane_b32 s0, v254, 56
	v_writelane_b32 v255, s79, 59
	v_writelane_b32 v255, s80, 60
	v_readlane_b32 s60, v252, 9
	v_readlane_b32 s61, v252, 10
	v_writelane_b32 v255, s81, 61
	v_readlane_b32 s1, v254, 57
	v_readlane_b32 s58, v252, 7
	v_readlane_b32 s59, v252, 8
	v_readlane_b32 s62, v252, 11
	v_readlane_b32 s63, v252, 12
	v_readlane_b32 s64, v252, 13
	v_readlane_b32 s65, v252, 14
	v_readlane_b32 s66, v252, 15
	v_readlane_b32 s67, v252, 16
	v_readlane_b32 s68, v252, 17
	v_readlane_b32 s69, v252, 18
	v_readlane_b32 s70, v252, 19
	v_readlane_b32 s71, v252, 20
	s_mov_b64 s[40:41], s[60:61]
	v_writelane_b32 v255, s82, 62
	s_andn2_b64 vcc, exec, s[0:1]
	v_readlane_b32 s5, v254, 58
	s_mov_b64 s[42:43], s[62:63]
	s_mov_b64 s[44:45], s[64:65]
	s_mov_b64 s[46:47], s[66:67]
	s_mov_b64 s[48:49], s[68:69]
	s_mov_b64 s[50:51], s[70:71]
	s_mov_b64 s[38:39], s[58:59]
	v_writelane_b32 v255, s83, 63
	s_waitcnt lgkmcnt(0)
	s_barrier
	v_readlane_b32 s57, v252, 6
	s_cbranch_vccz .LBB0_157

; __device__ __forceinline__ f32x16 mfma32(bf16x8 a, bf16x8 b, f32x16 c) { return __builtin_amdgcn_mfma_f32_32x32x16_bf16(a, b, c, 0, 0, 0); }
; template <int MODE> ...
;     ...
;     if (MODE == MODE_FOX) active = (64 * kt <= wtmax);
;     const bool selbit = (MODE == MODE_SEL) ? ((((kt < 32) ? (mlo >> kt) : (mhi >> (kt - 32))) & 1u) != 0u) : true;
;     if (MODE == MODE_SEL) active = __any(selbit) != 0;
;     if (active) {
;         const lptr Kt = L + A_KT + buf * 9216, Vt = L + A_VT + vcur * 12288;
;         f32x16 s0, s1;
; #pragma unroll
;         for (int s4 = 0; s4 < 4; ++s4) {
;             const bf16x8 a0 = lds_ld<bf16x8>(Kt + n * KP + s4 * 32 + hl * 16);
;             const bf16x8 a1 = lds_ld<bf16x8>(Kt + (32 + n) * KP + s4 * 32 + hl * 16);
;             if (s4 == 0) { s0 = mfma32(a0, qf[0], negm); s1 = mfma32(a1, qf[0], negm); }
;             else { s0 = mfma32(a0, qf[s4], s0); s1 = mfma32(a1, qf[s4], s1); }
;         }
.LBB0_178:
	s_cmp_eq_u32 s99, 0
	s_cbranch_scc1 .Lstg_f0
	s_sleep 4
